# counted vmcnt waits in GLA scan loop (2-step load flight); rotate TR GEMM tile assignment by 107 blocks to balance with in-proj; plus earlier epilogue load hoists
# speedup vs baseline: 1.0074x; 1.0043x over previous
; __global__ void __launch_bounds__(512, 2) fwd_megakernel(Params p) {
;     ...
;     { pg8::Gemm g{(const bf16_t*)(ws + OFF_W0 + W_TR0), hb, DM}; pg8::Order S; S.init(4, NMT, G, bx, 0);
;       pg8::EpiScaleT E{(bf16_t*)(ws + OFF_TR), ssq}; pg8::gemm_phase(lds, g, S, E, wv); }
.LBB0_327:
	s_cmpk_lg_i32 s96, 0x100
	s_cbranch_scc1 .Ltr_rot_in
	s_add_i32 s86, s86, 0x6b
	s_and_b32 s86, s86, 0xff

; __global__ void __launch_bounds__(512, 2) fwd_megakernel(Params p) {
;     ...
;     { pg8::Gemm g{(const bf16_t*)(ws + OFF_W0 + W_TR0), hb, DM}; pg8::Order S; S.init(4, NMT, G, bx, 0);
;       pg8::EpiScaleT E{(bf16_t*)(ws + OFF_TR), ssq}; pg8::gemm_phase(lds, g, S, E, wv); }
.LBB0_385:
	s_cmpk_lg_i32 s96, 0x100
	s_cbranch_scc1 .Ltr_rot_out
	s_add_i32 s86, s86, 0x95
	s_and_b32 s86, s86, 0xff

.LBB0_1858:
	s_add_i32 s98, s66, -8
	s_cmpk_gt_u32 s98, 0xf6
	s_cbranch_scc1 .Lgs_a_slow
	s_cmp_eq_u64 s[20:21], 0
	s_cbranch_scc1 .Lgs_a_ow
	s_mov_b32 s98, 1
	s_waitcnt vmcnt(7)
	s_branch .Lgs_a_go
.Lgs_a_ow:
	s_mov_b32 s98, 2
	s_waitcnt vmcnt(25)
	s_branch .Lgs_a_go
.Lgs_a_slow:
	s_mov_b32 s98, 0
	s_waitcnt vmcnt(1)
.Lgs_a_go:
	ds_write_b128 v199, v[8:11] offset:48640
	ds_write_b128 v200, v[16:19] offset:48640
	ds_write_b128 v201, v[20:23] offset:48640
	ds_write_b128 v202, v[28:31] offset:48640
	ds_write_b128 v211, v[36:39]
	s_and_saveexec_b64 s[28:29], s[8:9]
	s_cbranch_execz .LBB0_1860
	ds_write_b16 v213, v12
	ds_write_b16_d16_hi v213, v12 offset:144
	ds_write_b16 v213, v13 offset:288
	ds_write_b16_d16_hi v213, v13 offset:432
	ds_write_b16 v213, v14 offset:576
	ds_write_b16_d16_hi v213, v14 offset:720
	ds_write_b16 v213, v15 offset:864
	ds_write_b16_d16_hi v213, v15 offset:1008
	ds_write_b32 v214, v204

.LBB0_1878:
	s_cmp_lg_u32 s98, 2
	s_cbranch_scc1 .Lgs_aq_go
	s_waitcnt vmcnt(22)

.LBB0_1881:
	s_waitcnt lgkmcnt(0)
	s_barrier
	s_cmp_eq_u32 s98, 1
	s_cbranch_scc1 .Lgs_b_st
	s_cmp_eq_u32 s98, 2
	s_cbranch_scc1 .Lgs_b_ow
	s_waitcnt vmcnt(0)
	s_branch .Lgs_b_go
.Lgs_b_st:
	s_waitcnt vmcnt(7)
	s_branch .Lgs_b_go
.Lgs_b_ow:
	s_waitcnt vmcnt(25)
.Lgs_b_go:
	ds_write_b128 v199, v[24:27]
	ds_write_b128 v200, v[32:35]
	ds_write_b128 v201, v[40:43]
	ds_write_b128 v202, v[108:111]
	ds_write_b128 v203, v[112:115] offset:38400
	s_and_saveexec_b64 s[30:31], s[8:9]
	s_cbranch_execz .LBB0_1886
	ds_write_b16 v218, v0 offset:33792
	ds_write_b16_d16_hi v218, v0 offset:33936
	ds_write_b16 v218, v1 offset:34080
	ds_write_b16_d16_hi v218, v1 offset:34224
	ds_write_b16 v218, v2 offset:34368
	ds_write_b16_d16_hi v218, v2 offset:34512
	ds_write_b16 v218, v3 offset:34656
	ds_write_b16_d16_hi v218, v3 offset:34800
	ds_write_b32 v219, v198 offset:47616
	s_or_b64 exec, exec, s[30:31]
	s_cmpk_gt_u32 s67, 0xfc
	s_cbranch_scc0 .LBB0_1887

; __global__ void __launch_bounds__(512, 2) fwd_megakernel(Params p) {
	.amdhsa_kernel _Z14fwd_megakernel6Params
		.amdhsa_group_segment_fixed_size 0
		.amdhsa_private_segment_fixed_size 0
		.amdhsa_kernarg_size 432
		.amdhsa_user_sgpr_count 2
		.amdhsa_user_sgpr_dispatch_ptr 0
		.amdhsa_user_sgpr_queue_ptr 0
		.amdhsa_user_sgpr_kernarg_segment_ptr 1
		.amdhsa_user_sgpr_dispatch_id 0
		.amdhsa_user_sgpr_kernarg_preload_length 0
		.amdhsa_user_sgpr_kernarg_preload_offset 0
		.amdhsa_user_sgpr_private_segment_size 0
		.amdhsa_uses_dynamic_stack 0
		.amdhsa_enable_private_segment 0
		.amdhsa_system_sgpr_workgroup_id_x 1
		.amdhsa_system_sgpr_workgroup_id_y 0
		.amdhsa_system_sgpr_workgroup_id_z 0
		.amdhsa_system_sgpr_workgroup_info 0
		.amdhsa_system_vgpr_workitem_id 2
		.amdhsa_next_free_vgpr 256
		.amdhsa_next_free_sgpr 100
		.amdhsa_accum_offset 256
		.amdhsa_reserve_vcc 1
		.amdhsa_float_round_mode_32 0
		.amdhsa_float_round_mode_16_64 0
		.amdhsa_float_denorm_mode_32 3
		.amdhsa_float_denorm_mode_16_64 3
		.amdhsa_dx10_clamp 1
		.amdhsa_ieee_mode 1
		.amdhsa_fp16_overflow 0
		.amdhsa_tg_split 0
		.amdhsa_exception_fp_ieee_invalid_op 0
		.amdhsa_exception_fp_denorm_src 0
		.amdhsa_exception_fp_ieee_div_zero 0
		.amdhsa_exception_fp_ieee_overflow 0
		.amdhsa_exception_fp_ieee_underflow 0
		.amdhsa_exception_fp_ieee_inexact 0
		.amdhsa_exception_int_div_zero 0
	.end_amdhsa_kernel

; __global__ void __launch_bounds__(512, 2) fwd_megakernel(Params p) {
amdhsa.kernels:
  - .agpr_count:     0
    .args:
      - .offset:         0
        .size:           176
        .value_kind:     by_value
      - .offset:         176
        .size:           4
        .value_kind:     hidden_block_count_x
      - .offset:         180
        .size:           4
        .value_kind:     hidden_block_count_y
      - .offset:         184
        .size:           4
        .value_kind:     hidden_block_count_z
      - .offset:         188
        .size:           2
        .value_kind:     hidden_group_size_x
      - .offset:         190
        .size:           2
        .value_kind:     hidden_group_size_y
      - .offset:         192
        .size:           2
        .value_kind:     hidden_group_size_z
      - .offset:         194
        .size:           2
        .value_kind:     hidden_remainder_x
      - .offset:         196
        .size:           2
        .value_kind:     hidden_remainder_y
      - .offset:         198
        .size:           2
        .value_kind:     hidden_remainder_z
      - .offset:         216
        .size:           8
        .value_kind:     hidden_global_offset_x
      - .offset:         224
        .size:           8
        .value_kind:     hidden_global_offset_y
      - .offset:         232
        .size:           8
        .value_kind:     hidden_global_offset_z
      - .offset:         240
        .size:           2
        .value_kind:     hidden_grid_dims
      - .offset:         264
        .size:           8
        .value_kind:     hidden_multigrid_sync_arg
      - .offset:         296
        .size:           4
        .value_kind:     hidden_dynamic_lds_size
    .group_segment_fixed_size: 0
    .kernarg_segment_align: 8
    .kernarg_segment_size: 432
    .language:       OpenCL C
    .language_version:
      - 2
      - 0
    .max_flat_workgroup_size: 512
    .name:           _Z14fwd_megakernel6Params
    .private_segment_fixed_size: 0
    .sgpr_count:     106
    .sgpr_spill_count: 64
    .symbol:         _Z14fwd_megakernel6Params.kd
    .uniform_work_group_size: 1
    .uses_dynamic_stack: false
    .vgpr_count:     256
    .vgpr_spill_count: 0
    .wavefront_size: 64
